# loop-edge edit: FF2 GEMM k-loop LDS address math hoisted above the vmcnt wait + barrier (on top of v27)
# speedup vs baseline: 1.0044x; 1.0011x over previous
; #define ROW4(accv, r, av)                                                                              \
;     accv[r][0] = MFMA16(av, b0, accv[r][0]); accv[r][1] = MFMA16(av, b1, accv[r][1]);                      \
;     accv[r][2] = MFMA16(av, b2, accv[r][2]); accv[r][3] = MFMA16(av, b3, accv[r][3]);
; template <int EPI>
; __device__ __forceinline__ void gemm_tile_dma(const bft* __restrict__ A, int lda, const bft* __restrict__ Bt, int K, int row0, int col0,
;                                               char* smem, const EpiArgs& e) {
;     ...
;   for (int kt = 0; kt < nk; ++kt) {
;     if (kt + 2 < nk) asm volatile("s_waitcnt vmcnt(8)" ::: "memory");
;     else if (kt + 1 < nk) asm volatile("s_waitcnt vmcnt(4)" ::: "memory");
;     else asm volatile("s_waitcnt vmcnt(0)" ::: "memory");
;     __builtin_amdgcn_s_barrier();
;     asm volatile("" ::: "memory");
;     const bool pf = kt + 3 < nk;
;     const unsigned so = (unsigned)(kt & 3) * GST;
;     bf16x8 a0, a1, a2, a3, b0, b1, b2, b3;
;     asm volatile(
;         "ds_read_b128 %0, %8\n\t"
;         "ds_read_b128 %1, %8 offset:1024\n\t"
;         "ds_read_b128 %2, %8 offset:2048\n\t"
;         "ds_read_b128 %3, %8 offset:3072\n\t"
;         "ds_read_b128 %4, %9\n\t"
;         "ds_read_b128 %5, %9 offset:1024\n\t"
;         "ds_read_b128 %6, %9 offset:2048\n\t"
;         "ds_read_b128 %7, %9 offset:3072\n\t"
;         "s_waitcnt lgkmcnt(0)"
;         : "=&v"(a0), "=&v"(a1), "=&v"(a2), "=&v"(a3), "=&v"(b0), "=&v"(b1), "=&v"(b2), "=&v"(b3)
;         : "v"(lds_a + so), "v"(lds_b + so)
;         : "memory");
;     ...
;     ROW4(accL, 0, a0) ROW4(accL, 1, a1)
;     if (pf) GEMM_DMA_A(kt + 3)
;     ROW4(accL, 2, a2) ROW4(accL, 3, a3)
;     asm volatile(
;         "ds_read_b128 %0, %4 offset:4096\n\t"
;         "ds_read_b128 %1, %4 offset:5120\n\t"
;         "ds_read_b128 %2, %4 offset:6144\n\t"
;         "ds_read_b128 %3, %4 offset:7168\n\t"
;         "s_waitcnt lgkmcnt(0)"
;         : "=&v"(a0), "=&v"(a1), "=&v"(a2), "=&v"(a3)
;         : "v"(lds_a + so)
;         : "memory");
;     ROW4(accH, 0, a0) ROW4(accH, 1, a1)
;     if (pf) GEMM_DMA_B(kt + 3)
;     ROW4(accH, 2, a2) ROW4(accH, 3, a3)
.LBB0_1328:
	s_and_b32 s34, s27, 0x18000
	v_add_u32_e32 v158, s34, v133
	v_or_b32_e32 v159, s34, v132
	s_add_i32 s34, s27, 0x18000
	s_waitcnt vmcnt(8)
	s_barrier
	ds_read_b128 v[134:137], v158
	ds_read_b128 v[138:141], v158 offset:1024
	ds_read_b128 v[142:145], v158 offset:2048
	ds_read_b128 v[146:149], v158 offset:3072
	ds_read_b128 v[150:153], v159
	ds_read_b128 v[154:157], v159 offset:1024
	ds_read_b128 v[162:165], v159 offset:2048
	ds_read_b128 v[166:169], v159 offset:3072
	s_waitcnt lgkmcnt(0)
	s_and_b32 s34, s34, 0x18000
	v_mfma_f32_16x16x32_bf16 v[124:127], v[134:137], v[150:153], v[124:127]
	s_mov_b64 s[38:39], 0x198000c0
	v_add_u32_e32 v159, s34, v190
	v_mfma_f32_16x16x32_bf16 v[120:123], v[134:137], v[154:157], v[120:123]
	v_readfirstlane_b32 s34, v159
	s_mov_b32 m0, s34
	v_mfma_f32_16x16x32_bf16 v[116:119], v[134:137], v[162:165], v[116:119]
	v_mfma_f32_16x16x32_bf16 v[108:111], v[134:137], v[166:169], v[108:111]
	v_lshl_add_u64 v[134:135], v[130:131], 0, s[12:13]
	v_lshl_add_u64 v[136:137], v[134:135], 0, s[38:39]
	s_mov_b64 s[38:39], 0x199000c0
	v_mfma_f32_16x16x32_bf16 v[104:107], v[138:141], v[150:153], v[104:107]
	v_lshl_add_u64 v[134:135], v[134:135], 0, s[38:39]
	global_load_lds_dwordx4 v[136:137], off
	v_mfma_f32_16x16x32_bf16 v[100:103], v[138:141], v[154:157], v[100:103]
	v_mfma_f32_16x16x32_bf16 v[96:99], v[138:141], v[162:165], v[96:99]
	v_mfma_f32_16x16x32_bf16 v[92:95], v[138:141], v[166:169], v[92:95]
	v_add_u32_e32 v138, 0x2000, v159
	s_nop 0
	v_readfirstlane_b32 s38, v138
	s_mov_b32 m0, s38
	v_mfma_f32_16x16x32_bf16 v[88:91], v[142:145], v[150:153], v[88:91]
	global_load_lds_dwordx4 v[134:135], off
	s_mov_b64 s[38:39], 0x3c7800c0
	v_mfma_f32_16x16x32_bf16 v[84:87], v[142:145], v[154:157], v[84:87]
	v_mfma_f32_16x16x32_bf16 v[80:83], v[142:145], v[162:165], v[80:83]
	v_mfma_f32_16x16x32_bf16 v[76:79], v[142:145], v[166:169], v[76:79]
	v_mfma_f32_16x16x32_bf16 v[72:75], v[146:149], v[150:153], v[72:75]
	v_mfma_f32_16x16x32_bf16 v[68:71], v[146:149], v[154:157], v[68:71]
	v_mfma_f32_16x16x32_bf16 v[64:67], v[146:149], v[162:165], v[64:67]
	v_mfma_f32_16x16x32_bf16 v[60:63], v[146:149], v[166:169], v[60:63]
	ds_read_b128 v[134:137], v158 offset:4096
	ds_read_b128 v[138:141], v158 offset:5120
	ds_read_b128 v[142:145], v158 offset:6144
	ds_read_b128 v[146:149], v158 offset:7168
	s_waitcnt lgkmcnt(0)
	s_nop 0
	v_mfma_f32_16x16x32_bf16 v[112:115], v[134:137], v[150:153], v[112:115]
	v_mfma_f32_16x16x32_bf16 v[0:3], v[134:137], v[154:157], v[0:3]
	v_mfma_f32_16x16x32_bf16 v[56:59], v[134:137], v[162:165], v[56:59]
	v_mfma_f32_16x16x32_bf16 v[4:7], v[134:137], v[166:169], v[4:7]
	v_lshl_add_u64 v[134:135], v[128:129], 0, s[12:13]
	v_lshl_add_u64 v[136:137], v[134:135], 0, s[38:39]
	s_mov_b64 s[38:39], 0x3c8800c0
	v_mfma_f32_16x16x32_bf16 v[52:55], v[138:141], v[150:153], v[52:55]
	v_lshl_add_u64 v[134:135], v[134:135], 0, s[38:39]
	s_add_u32 s12, s12, 64
	s_addc_u32 s13, s13, 0
	v_mfma_f32_16x16x32_bf16 v[8:11], v[138:141], v[154:157], v[8:11]
	s_add_i32 s27, s27, 0x8000
	s_cmpk_eq_i32 s12, 0x1f40
	v_mfma_f32_16x16x32_bf16 v[48:51], v[138:141], v[162:165], v[48:51]
	v_mfma_f32_16x16x32_bf16 v[12:15], v[138:141], v[166:169], v[12:15]
	v_add_u32_e32 v138, 0x4000, v159
	v_add_u32_e32 v139, 0x6000, v159
	v_readfirstlane_b32 s34, v138
	v_readfirstlane_b32 s38, v139
	s_mov_b32 m0, s34
	v_mfma_f32_16x16x32_bf16 v[44:47], v[142:145], v[150:153], v[44:47]
	global_load_lds_dwordx4 v[136:137], off
	s_mov_b32 m0, s38
	v_mfma_f32_16x16x32_bf16 v[16:19], v[142:145], v[154:157], v[16:19]
	global_load_lds_dwordx4 v[134:135], off
	v_mfma_f32_16x16x32_bf16 v[40:43], v[142:145], v[162:165], v[40:43]
	v_mfma_f32_16x16x32_bf16 v[20:23], v[142:145], v[166:169], v[20:23]
	v_mfma_f32_16x16x32_bf16 v[36:39], v[146:149], v[150:153], v[36:39]
	v_mfma_f32_16x16x32_bf16 v[24:27], v[146:149], v[154:157], v[24:27]
	v_mfma_f32_16x16x32_bf16 v[32:35], v[146:149], v[162:165], v[32:35]
	v_mfma_f32_16x16x32_bf16 v[28:31], v[146:149], v[166:169], v[28:31]
	s_cbranch_scc0 .LBB0_1328
	s_waitcnt vmcnt(8)
	s_barrier
	v_add_u32_e32 v158, 0x8000, v133
	v_or_b32_e32 v159, 0x8000, v132
	ds_read_b128 v[128:131], v158
	ds_read_b128 v[134:137], v158 offset:1024
	ds_read_b128 v[138:141], v158 offset:2048
	ds_read_b128 v[142:145], v158 offset:3072
	ds_read_b128 v[146:149], v159
	ds_read_b128 v[150:153], v159 offset:1024
	ds_read_b128 v[154:157], v159 offset:2048
	ds_read_b128 v[162:165], v159 offset:3072
	s_waitcnt lgkmcnt(0)
	v_or_b32_e32 v159, 0x10000, v132
	v_mfma_f32_16x16x32_bf16 v[124:127], v[128:131], v[146:149], v[124:127]
	v_add_u32_e32 v160, 0x18000, v133
	v_or_b32_e32 v132, 0x18000, v132
	s_movk_i32 s12, 0x4400
	v_mfma_f32_16x16x32_bf16 v[120:123], v[128:131], v[150:153], v[120:123]
	s_mul_i32 s13, s15, 0xf0f0f0f1
	v_and_b32_e32 v183, 63, v188
	v_mfma_f32_16x16x32_bf16 v[116:119], v[128:131], v[154:157], v[116:119]
	v_mfma_f32_16x16x32_bf16 v[108:111], v[128:131], v[162:165], v[108:111]
	v_mfma_f32_16x16x32_bf16 v[104:107], v[134:137], v[146:149], v[104:107]
	v_mfma_f32_16x16x32_bf16 v[100:103], v[134:137], v[150:153], v[100:103]
	v_mfma_f32_16x16x32_bf16 v[96:99], v[134:137], v[154:157], v[96:99]
	v_mfma_f32_16x16x32_bf16 v[92:95], v[134:137], v[162:165], v[92:95]
	v_mfma_f32_16x16x32_bf16 v[88:91], v[138:141], v[146:149], v[88:91]
	v_mfma_f32_16x16x32_bf16 v[84:87], v[138:141], v[150:153], v[84:87]
	v_mfma_f32_16x16x32_bf16 v[80:83], v[138:141], v[154:157], v[80:83]
	v_mfma_f32_16x16x32_bf16 v[76:79], v[138:141], v[162:165], v[76:79]
	v_mfma_f32_16x16x32_bf16 v[72:75], v[142:145], v[146:149], v[72:75]
	v_mfma_f32_16x16x32_bf16 v[68:71], v[142:145], v[150:153], v[68:71]
	v_mfma_f32_16x16x32_bf16 v[64:67], v[142:145], v[154:157], v[64:67]
	v_mfma_f32_16x16x32_bf16 v[60:63], v[142:145], v[162:165], v[60:63]
	ds_read_b128 v[128:131], v158 offset:4096
	ds_read_b128 v[134:137], v158 offset:5120
	ds_read_b128 v[138:141], v158 offset:6144
	ds_read_b128 v[142:145], v158 offset:7168
	s_waitcnt lgkmcnt(0)
	s_waitcnt vmcnt(4)
	s_barrier
; #define ROW4(accv, r, av)                                                                              \
;     accv[r][0] = MFMA16(av, b0, accv[r][0]); accv[r][1] = MFMA16(av, b1, accv[r][1]);                      \
;     accv[r][2] = MFMA16(av, b2, accv[r][2]); accv[r][3] = MFMA16(av, b3, accv[r][3]);
; template <int EPI>
; __device__ __forceinline__ void gemm_tile_dma(const bft* __restrict__ A, int lda, const bft* __restrict__ Bt, int K, int row0, int col0,
;                                               char* smem, const EpiArgs& e) {
;     ...
;   for (int kt = 0; kt < nk; ++kt) {
;     if (kt + 2 < nk) asm volatile("s_waitcnt vmcnt(8)" ::: "memory");
;     else if (kt + 1 < nk) asm volatile("s_waitcnt vmcnt(4)" ::: "memory");
;     else asm volatile("s_waitcnt vmcnt(0)" ::: "memory");
;     __builtin_amdgcn_s_barrier();
;     asm volatile("" ::: "memory");
;     const bool pf = kt + 3 < nk;
;     const unsigned so = (unsigned)(kt & 3) * GST;
;     bf16x8 a0, a1, a2, a3, b0, b1, b2, b3;
;     asm volatile(
;         "ds_read_b128 %0, %8\n\t"
;         "ds_read_b128 %1, %8 offset:1024\n\t"
;         "ds_read_b128 %2, %8 offset:2048\n\t"
;         "ds_read_b128 %3, %8 offset:3072\n\t"
;         "ds_read_b128 %4, %9\n\t"
;         "ds_read_b128 %5, %9 offset:1024\n\t"
;         "ds_read_b128 %6, %9 offset:2048\n\t"
;         "ds_read_b128 %7, %9 offset:3072\n\t"
;         "s_waitcnt lgkmcnt(0)"
;         : "=&v"(a0), "=&v"(a1), "=&v"(a2), "=&v"(a3), "=&v"(b0), "=&v"(b1), "=&v"(b2), "=&v"(b3)
;         : "v"(lds_a + so), "v"(lds_b + so)
;         : "memory");
;     ...
;     ROW4(accL, 0, a0) ROW4(accL, 1, a1)
;     if (pf) GEMM_DMA_A(kt + 3)
;     ROW4(accL, 2, a2) ROW4(accL, 3, a3)
;     asm volatile(
;         "ds_read_b128 %0, %4 offset:4096\n\t"
;         "ds_read_b128 %1, %4 offset:5120\n\t"
;         "ds_read_b128 %2, %4 offset:6144\n\t"
;         "ds_read_b128 %3, %4 offset:7168\n\t"
;         "s_waitcnt lgkmcnt(0)"
;         : "=&v"(a0), "=&v"(a1), "=&v"(a2), "=&v"(a3)
;         : "v"(lds_a + so)
;         : "memory");
;     ROW4(accH, 0, a0) ROW4(accH, 1, a1)
;     if (pf) GEMM_DMA_B(kt + 3)
;     ROW4(accH, 2, a2) ROW4(accH, 3, a3)
	v_mfma_f32_16x16x32_bf16 v[112:115], v[128:131], v[146:149], v[112:115]
	v_add_u32_e32 v158, 0x10000, v133
	v_mfma_f32_16x16x32_bf16 v[0:3], v[128:131], v[150:153], v[0:3]
	v_mfma_f32_16x16x32_bf16 v[56:59], v[128:131], v[154:157], v[56:59]
	v_mfma_f32_16x16x32_bf16 v[4:7], v[128:131], v[162:165], v[4:7]
	v_mfma_f32_16x16x32_bf16 v[52:55], v[134:137], v[146:149], v[52:55]
	v_mfma_f32_16x16x32_bf16 v[8:11], v[134:137], v[150:153], v[8:11]
	v_mfma_f32_16x16x32_bf16 v[48:51], v[134:137], v[154:157], v[48:51]
	v_mfma_f32_16x16x32_bf16 v[12:15], v[134:137], v[162:165], v[12:15]
	v_mfma_f32_16x16x32_bf16 v[44:47], v[138:141], v[146:149], v[44:47]
	v_mfma_f32_16x16x32_bf16 v[16:19], v[138:141], v[150:153], v[16:19]
	v_mfma_f32_16x16x32_bf16 v[128:131], v[138:141], v[154:157], v[40:43]
	v_mfma_f32_16x16x32_bf16 v[20:23], v[138:141], v[162:165], v[20:23]
	v_mfma_f32_16x16x32_bf16 v[134:137], v[142:145], v[146:149], v[36:39]
	v_mfma_f32_16x16x32_bf16 v[24:27], v[142:145], v[150:153], v[24:27]
	v_mfma_f32_16x16x32_bf16 v[32:35], v[142:145], v[154:157], v[32:35]
	v_mfma_f32_16x16x32_bf16 v[28:31], v[142:145], v[162:165], v[28:31]
	ds_read_b128 v[138:141], v158
	ds_read_b128 v[142:145], v158 offset:1024
	ds_read_b128 v[146:149], v158 offset:2048
	ds_read_b128 v[150:153], v158 offset:3072
	ds_read_b128 v[154:157], v159
	ds_read_b128 v[40:43], v159 offset:1024
	ds_read_b128 v[162:165], v159 offset:2048
	ds_read_b128 v[36:39], v159 offset:3072
	s_waitcnt lgkmcnt(0)
	s_nop 0
	v_mfma_f32_16x16x32_bf16 v[124:127], v[138:141], v[154:157], v[124:127]
	v_mfma_f32_16x16x32_bf16 v[120:123], v[138:141], v[40:43], v[120:123]
	v_mfma_f32_16x16x32_bf16 v[116:119], v[138:141], v[162:165], v[116:119]
	v_mfma_f32_16x16x32_bf16 v[108:111], v[138:141], v[36:39], v[108:111]
	v_mfma_f32_16x16x32_bf16 v[104:107], v[142:145], v[154:157], v[104:107]
	v_mfma_f32_16x16x32_bf16 v[100:103], v[142:145], v[40:43], v[100:103]
	v_mfma_f32_16x16x32_bf16 v[96:99], v[142:145], v[162:165], v[96:99]
	v_mfma_f32_16x16x32_bf16 v[138:141], v[142:145], v[36:39], v[92:95]
	v_mfma_f32_16x16x32_bf16 v[142:145], v[146:149], v[154:157], v[88:91]
	v_mfma_f32_16x16x32_bf16 v[178:181], v[146:149], v[40:43], v[84:87]
	v_mfma_f32_16x16x32_bf16 v[184:187], v[146:149], v[162:165], v[80:83]
	v_mfma_f32_16x16x32_bf16 v[76:79], v[146:149], v[36:39], v[76:79]
	v_mfma_f32_16x16x32_bf16 v[192:195], v[150:153], v[154:157], v[72:75]
	v_mfma_f32_16x16x32_bf16 v[198:201], v[150:153], v[40:43], v[68:71]
	v_mfma_f32_16x16x32_bf16 v[206:209], v[150:153], v[36:39], v[60:63]
	ds_read_b128 v[88:91], v158 offset:4096
	ds_read_b128 v[84:87], v158 offset:5120
	ds_read_b128 v[68:71], v158 offset:6144
	ds_read_b128 v[60:63], v158 offset:7168
	s_waitcnt lgkmcnt(0)
	s_waitcnt vmcnt(0)
	s_barrier
	v_mfma_f32_16x16x32_bf16 v[210:213], v[88:91], v[154:157], v[112:115]
	v_mfma_f32_16x16x32_bf16 v[202:205], v[150:153], v[162:165], v[64:67]
	v_mfma_f32_16x16x32_bf16 v[64:67], v[88:91], v[162:165], v[56:59]
	v_mfma_f32_16x16x32_bf16 v[214:217], v[84:87], v[154:157], v[52:55]
	v_mfma_f32_16x16x32_bf16 v[72:75], v[84:87], v[162:165], v[48:51]
	v_mfma_f32_16x16x32_bf16 v[80:83], v[68:71], v[162:165], v[128:131]
	v_mfma_f32_16x16x32_bf16 v[56:59], v[60:63], v[162:165], v[32:35]
	ds_read_b128 v[32:35], v160
	ds_read_b128 v[112:115], v160 offset:1024
	ds_read_b128 v[128:131], v160 offset:2048
	ds_read_b128 v[222:225], v160 offset:3072
	ds_read_b128 v[226:229], v132
	ds_read_b128 v[52:55], v132 offset:1024
	ds_read_b128 v[92:95], v132 offset:2048
	ds_read_b128 v[48:51], v132 offset:3072
	s_waitcnt lgkmcnt(0)
	s_nop 0
	v_mfma_f32_16x16x32_bf16 v[148:151], v[112:115], v[48:51], v[138:141]
	v_mfma_f32_16x16x32_bf16 v[144:147], v[128:131], v[226:229], v[142:145]
	v_mfma_f32_16x16x32_bf16 v[140:143], v[128:131], v[52:55], v[178:181]
	s_nop 2
	v_lshrrev_b32_e32 v178, 6, v188
	v_mfma_f32_16x16x32_bf16 v[44:47], v[68:71], v[154:157], v[44:47]
	v_mfma_f32_16x16x32_bf16 v[218:221], v[60:63], v[154:157], v[134:137]
	v_mfma_f32_16x16x32_bf16 v[166:169], v[32:35], v[48:51], v[108:111]
	v_mfma_f32_16x16x32_bf16 v[162:165], v[112:115], v[226:229], v[104:107]
	v_mfma_f32_16x16x32_bf16 v[156:159], v[112:115], v[52:55], v[100:103]
	v_mfma_f32_16x16x32_bf16 v[152:155], v[112:115], v[92:95], v[96:99]
	ds_read_b128 v[112:115], v160 offset:4096
	ds_read_b128 v[108:111], v160 offset:5120
	ds_read_b128 v[104:107], v160 offset:6144
	ds_read_b128 v[100:103], v160 offset:7168
	s_waitcnt lgkmcnt(0)
	v_and_b32_e32 v160, 0xc0, v188
	s_waitcnt vmcnt(0) lgkmcnt(0)
	v_mfma_f32_16x16x32_bf16 v[136:139], v[128:131], v[92:95], v[184:187]
	s_barrier
; template <int EPI>
; DI void epilogue_tile(const EpiArgs& e, int row0, int wrow, int wcol, f32x4 (&acc)[4][4], char* smem, const float* rsm, int wave, int lane,
;                       bool final_sync = true) {
;     ...
;       if constexpr (EPI == EPI_RES) {
;         const float gg = e.gate[(size_t)mi_mod * 6144 + col], bb = e.bias[col];
; #pragma unroll
;         for (int j = 0; j < 4; ++j) v[j] = gg * (v[j] + bb);
;       }
;       if constexpr (EPI == EPI_FF1) {
;         const float bb = e.bias[col];
; #pragma unroll
;         for (int j = 0; j < 4; ++j) { const float t = fmaxf(v[j] + bb, 0.f); v[j] = t * t; }
;       }
;       if (transposed) {
;         *(f32x4*)(stage + lcol * STG + lrow) = (f32x4){v[0], v[1], v[2], v[3]};
;       } else {
; #pragma unroll
;         for (int j = 0; j < 4; ++j) stage[(lrow + j) * STG + lcol] = v[j];
;       }
	v_mfma_f32_16x16x32_bf16 v[132:135], v[128:131], v[48:51], v[76:79]
	v_mfma_f32_16x16x32_bf16 v[128:131], v[222:225], v[226:229], v[192:195]
	s_nop 2
	v_mul_lo_u32 v195, v178, s12
	s_mul_hi_u32 s12, s16, 0xf0f0f10
	v_mfma_f32_16x16x32_bf16 v[96:99], v[112:115], v[226:229], v[210:213]
	s_mulk_i32 s12, 0x6000
	v_mov_b32_e32 v178, 0x60000
	v_lshl_or_b32 v192, v182, 2, v195
	v_or_b32_e32 v211, s17, v160
	v_alignbit_b32 v160, s13, s13, 8
	s_mov_b32 s13, 0xf0f0f
	v_cmp_lt_u32_e32 vcc, s13, v160
	v_mov_b32_e32 v160, s12
	v_mfma_f32_16x16x32_bf16 v[76:79], v[108:111], v[226:229], v[214:217]
	v_cndmask_b32_e32 v160, v178, v160, vcc
	v_lshl_add_u64 v[186:187], s[10:11], 0, v[160:161]
	v_or_b32_e32 v160, v211, v182
	v_lshlrev_b32_e32 v160, 2, v160
	v_readfirstlane_b32 s12, v186
	v_readfirstlane_b32 s13, v187
	global_load_dword v215, v160, s[6:7]
	v_mfma_f32_16x16x32_bf16 v[230:233], v[32:35], v[226:229], v[124:127]
	v_bfe_u32 v212, v188, 2, 4
	v_lshl_add_u64 v[178:179], v[186:187], 0, v[160:161]
	v_lshl_add_u64 v[180:181], s[6:7], 0, v[160:161]
	global_load_dword v214, v160, s[12:13]
	v_mfma_f32_16x16x32_bf16 v[124:127], v[222:225], v[52:55], v[198:201]
	s_waitcnt vmcnt(1)
	s_nop 1
	v_add_f32_e32 v160, v230, v215
	v_and_b32_e32 v198, 12, v212
	v_or_b32_e32 v199, 48, v183
	v_add_f32_e32 v183, v231, v215
	v_add_f32_e32 v184, v232, v215
	s_waitcnt vmcnt(0)
	v_mul_f32_e32 v160, v214, v160
	v_mad_u32_u24 v213, v198, s35, v192
	v_mul_f32_e32 v183, v214, v183
	v_mul_f32_e32 v184, v214, v184
	ds_write_b32 v213, v160
	ds_write_b32 v213, v183 offset:272
	ds_write_b32 v213, v184 offset:544
	v_add_lshl_u32 v160, v211, v182, 2
	global_load_dword v216, v160, s[12:13] offset:64
	global_load_dword v217, v160, s[6:7] offset:64
	v_mfma_f32_16x16x32_bf16 v[174:177], v[32:35], v[52:55], v[120:123]
	v_add_f32_e32 v185, v233, v215
	v_or_b32_e32 v200, 3, v212
	v_mul_f32_e32 v185, v214, v185
	v_mad_u32_u24 v201, v200, s35, v192
	ds_write_b32 v201, v185
	v_mfma_f32_16x16x32_bf16 v[170:173], v[32:35], v[92:95], v[116:119]
	v_lshl_add_u64 v[182:183], v[186:187], 0, v[160:161]
	v_lshl_add_u64 v[184:185], s[6:7], 0, v[160:161]
	v_lshl_or_b32 v191, v199, 2, v195
	v_add_f32_e32 v162, v162, v215
	v_add_f32_e32 v163, v163, v215
	v_mul_f32_e32 v162, v214, v162
	v_mul_f32_e32 v163, v214, v163
	v_add_f32_e32 v164, v164, v215
	v_mul_f32_e32 v164, v214, v164
	v_add_f32_e32 v165, v165, v215
	v_mul_f32_e32 v165, v214, v165
	v_add_f32_e32 v144, v144, v215
	v_add_f32_e32 v145, v145, v215
	v_mul_f32_e32 v144, v214, v144
	v_mul_f32_e32 v145, v214, v145
	v_add_f32_e32 v146, v146, v215
	v_mfma_f32_16x16x32_bf16 v[120:123], v[222:225], v[92:95], v[202:205]
	v_mul_f32_e32 v146, v214, v146
	v_add_f32_e32 v147, v147, v215
	v_mul_f32_e32 v147, v214, v147
	v_mfma_f32_16x16x32_bf16 v[116:119], v[222:225], v[48:51], v[206:209]
	v_add_f32_e32 v128, v128, v215
	v_add_f32_e32 v129, v129, v215
	v_mul_f32_e32 v128, v214, v128
	v_mul_f32_e32 v129, v214, v129
	v_add_f32_e32 v130, v130, v215
	v_mul_f32_e32 v130, v214, v130
	v_add_f32_e32 v131, v131, v215
	v_mul_f32_e32 v131, v214, v131
	v_mfma_f32_16x16x32_bf16 v[44:47], v[104:107], v[226:229], v[44:47]
	v_mul_u32_u24_e32 v193, 0x110, v198
	v_mul_u32_u24_e32 v194, 0x110, v200
	s_waitcnt vmcnt(0)
	v_add_f32_e32 v174, v174, v217
	v_mul_f32_e32 v174, v216, v174
	v_add_f32_e32 v175, v175, v217
	v_add_f32_e32 v176, v176, v217
	v_add_f32_e32 v177, v177, v217
	v_mul_f32_e32 v175, v216, v175
	v_mul_f32_e32 v176, v216, v176
	v_mul_f32_e32 v177, v216, v177
	ds_write_b32 v213, v174 offset:64
	ds_write_b32 v213, v175 offset:336
	ds_write_b32 v213, v176 offset:608
	ds_write_b32 v201, v177 offset:64
	global_load_dword v174, v160, s[12:13] offset:128
	global_load_dword v175, v160, s[6:7] offset:128
	v_mad_u32_u24 v177, v198, s35, v191
	v_add_f32_e32 v156, v156, v217
	v_mul_f32_e32 v156, v216, v156
	v_add_f32_e32 v157, v157, v217
	v_add_f32_e32 v158, v158, v217
	v_add_f32_e32 v159, v159, v217
	v_mul_f32_e32 v157, v216, v157
	v_mul_f32_e32 v158, v216, v158
	v_mul_f32_e32 v159, v216, v159
	v_add_f32_e32 v140, v140, v217
	v_mul_f32_e32 v140, v216, v140
	v_add_f32_e32 v141, v141, v217
	v_add_f32_e32 v142, v142, v217
	v_add_f32_e32 v143, v143, v217
	v_mul_f32_e32 v141, v216, v141
	v_mul_f32_e32 v142, v216, v142
	v_mul_f32_e32 v143, v216, v143
	v_add_f32_e32 v124, v124, v217
	v_mul_f32_e32 v124, v216, v124
	v_add_f32_e32 v125, v125, v217
	v_add_f32_e32 v126, v126, v217
	v_add_f32_e32 v127, v127, v217
	v_mul_f32_e32 v125, v216, v125
	v_mul_f32_e32 v126, v216, v126
	v_mul_f32_e32 v127, v216, v127
	v_mfma_f32_16x16x32_bf16 v[32:35], v[100:103], v[226:229], v[218:221]
	s_waitcnt vmcnt(0)
; template <int EPI>
; DI void epilogue_tile(const EpiArgs& e, int row0, int wrow, int wcol, f32x4 (&acc)[4][4], char* smem, const float* rsm, int wave, int lane,
;                       bool final_sync = true) {
;     ...
;       if constexpr (EPI == EPI_RES) {
;         const float gg = e.gate[(size_t)mi_mod * 6144 + col], bb = e.bias[col];
; #pragma unroll
;         for (int j = 0; j < 4; ++j) v[j] = gg * (v[j] + bb);
;       }
;       if constexpr (EPI == EPI_FF1) {
;         const float bb = e.bias[col];
; #pragma unroll
;         for (int j = 0; j < 4; ++j) { const float t = fmaxf(v[j] + bb, 0.f); v[j] = t * t; }
;       }
;       if (transposed) {
;         *(f32x4*)(stage + lcol * STG + lrow) = (f32x4){v[0], v[1], v[2], v[3]};
;       } else {
; #pragma unroll
;         for (int j = 0; j < 4; ++j) stage[(lrow + j) * STG + lcol] = v[j];
;       }
;     }
;   const int rr = lane >> 3, c8 = (lane & 7) * 8;
; #pragma unroll 4
;   for (int it = 0; it < 8; ++it) {
;     const int sr = it * 8 + rr;
;     const f32x4 v0 = *(const f32x4*)(stage + sr * STG + c8);
;     const f32x4 v1 = *(const f32x4*)(stage + sr * STG + c8 + 4);
;     if constexpr (EPI == EPI_RES) {
;       bft* px = (bft*)(e.ws + OFF_XS) + (size_t)(wrow + sr) * D + wcol + c8;
	v_add_f32_e32 v160, v170, v175
	v_mul_f32_e32 v160, v174, v160
	v_add_f32_e32 v170, v171, v175
	v_add_f32_e32 v171, v172, v175
	v_add_f32_e32 v172, v173, v175
	v_mul_f32_e32 v170, v174, v170
	v_mul_f32_e32 v171, v174, v171
	v_mul_f32_e32 v172, v174, v172
	ds_write_b32 v213, v160 offset:128
	ds_write_b32 v213, v170 offset:400
	ds_write_b32 v213, v171 offset:672
	ds_write_b32 v201, v172 offset:128
	v_or_b32_e32 v160, v211, v199
	v_lshlrev_b32_e32 v160, 2, v160
	v_lshl_add_u64 v[170:171], v[186:187], 0, v[160:161]
	global_load_dword v176, v160, s[12:13]
	v_lshl_add_u64 v[172:173], s[6:7], 0, v[160:161]
	global_load_dword v160, v160, s[6:7]
	v_add_f32_e32 v152, v152, v175
	v_mul_f32_e32 v152, v174, v152
	v_add_f32_e32 v153, v153, v175
	v_add_f32_e32 v154, v154, v175
	v_add_f32_e32 v155, v155, v175
	v_mul_f32_e32 v153, v174, v153
	v_mul_f32_e32 v154, v174, v154
	v_mul_f32_e32 v155, v174, v155
	v_add_f32_e32 v136, v136, v175
	v_mul_f32_e32 v136, v174, v136
	v_add_f32_e32 v137, v137, v175
	v_add_f32_e32 v138, v138, v175
	v_add_f32_e32 v139, v139, v175
	v_mul_f32_e32 v137, v174, v137
	v_mul_f32_e32 v138, v174, v138
	v_mul_f32_e32 v139, v174, v139
	v_add_f32_e32 v120, v120, v175
	v_mul_f32_e32 v120, v174, v120
	v_add_f32_e32 v121, v121, v175
	v_add_f32_e32 v122, v122, v175
	v_add_f32_e32 v123, v123, v175
	v_mul_f32_e32 v121, v174, v121
	v_mul_f32_e32 v122, v174, v122
	v_mul_f32_e32 v123, v174, v123
	s_mov_b32 s12, 0
	s_waitcnt vmcnt(0)
	v_add_f32_e32 v166, v166, v160
	v_add_f32_e32 v167, v167, v160
	v_mul_f32_e32 v166, v176, v166
	v_mul_f32_e32 v167, v176, v167
	v_add_f32_e32 v168, v168, v160
	v_add_f32_e32 v169, v169, v160
	v_mul_f32_e32 v168, v176, v168
	v_mul_f32_e32 v169, v176, v169
	ds_write2_b32 v177, v166, v167 offset1:68
	ds_write_b32 v177, v168 offset:544
	v_mad_u32_u24 v166, v200, s35, v191
	ds_write_b32 v166, v169
	ds_write_b32 v213, v162 offset:4352
	ds_write_b32 v213, v163 offset:4624
	ds_write_b32 v213, v164 offset:4896
	v_or_b32_e32 v163, 19, v212
	v_mad_u32_u24 v164, v163, s35, v192
	v_add_f32_e32 v148, v148, v160
	v_add_f32_e32 v149, v149, v160
	ds_write_b32 v164, v165
	ds_write_b32 v213, v156 offset:4416
	ds_write_b32 v213, v157 offset:4688
	ds_write_b32 v213, v158 offset:4960
	ds_write_b32 v164, v159 offset:64
	ds_write_b32 v213, v152 offset:4480
	ds_write_b32 v213, v153 offset:4752
	ds_write_b32 v213, v154 offset:5024
	ds_write_b32 v164, v155 offset:128
	v_mul_f32_e32 v148, v176, v148
	v_mul_f32_e32 v149, v176, v149
	v_add_f32_e32 v150, v150, v160
	v_add_f32_e32 v151, v151, v160
	v_add_u32_e32 v152, 0x1000, v177
	v_mul_f32_e32 v150, v176, v150
	v_mul_f32_e32 v151, v176, v151
	ds_write2_b32 v152, v148, v149 offset0:64 offset1:132
	ds_write_b32 v177, v150 offset:4896
	v_mad_u32_u24 v148, v163, s35, v191
	ds_write_b32 v148, v151
	ds_write_b32 v213, v144 offset:8704
	ds_write_b32 v213, v145 offset:8976
	ds_write_b32 v213, v146 offset:9248
	v_or_b32_e32 v145, 35, v212
	v_mad_u32_u24 v146, v145, s35, v192
	v_add_f32_e32 v132, v132, v160
	v_add_f32_e32 v133, v133, v160
	ds_write_b32 v146, v147
	ds_write_b32 v213, v140 offset:8768
	ds_write_b32 v213, v141 offset:9040
	ds_write_b32 v213, v142 offset:9312
	ds_write_b32 v146, v143 offset:64
	ds_write_b32 v213, v136 offset:8832
	ds_write_b32 v213, v137 offset:9104
	ds_write_b32 v213, v138 offset:9376
	ds_write_b32 v146, v139 offset:128
	v_mul_f32_e32 v132, v176, v132
	v_mul_f32_e32 v133, v176, v133
	v_add_f32_e32 v134, v134, v160
	v_add_f32_e32 v135, v135, v160
	v_add_u32_e32 v136, 0x2000, v177
	v_mul_f32_e32 v134, v176, v134
	v_mul_f32_e32 v135, v176, v135
	ds_write2_b32 v136, v132, v133 offset0:128 offset1:196
	ds_write_b32 v177, v134 offset:9248
	v_mad_u32_u24 v132, v145, s35, v191
	ds_write_b32 v132, v135
	ds_write_b32 v213, v128 offset:13056
	ds_write_b32 v213, v129 offset:13328
	ds_write_b32 v213, v130 offset:13600
	v_or_b32_e32 v129, 51, v212
	v_mad_u32_u24 v130, v129, s35, v192
	v_add_f32_e32 v116, v116, v160
	v_add_f32_e32 v117, v117, v160
	ds_write_b32 v130, v131
	ds_write_b32 v213, v124 offset:13120
	ds_write_b32 v213, v125 offset:13392
	ds_write_b32 v213, v126 offset:13664
	ds_write_b32 v130, v127 offset:64
	ds_write_b32 v213, v120 offset:13184
	ds_write_b32 v213, v121 offset:13456
	ds_write_b32 v213, v122 offset:13728
	ds_write_b32 v130, v123 offset:128
	v_mul_f32_e32 v116, v176, v116
	v_mul_f32_e32 v117, v176, v117
	v_add_f32_e32 v118, v118, v160
	v_add_f32_e32 v119, v119, v160
	v_add_u32_e32 v120, 0x3200, v177
	v_mul_f32_e32 v118, v176, v118
	v_mul_f32_e32 v119, v176, v119
	ds_write2_b32 v120, v116, v117 offset0:64 offset1:132
	ds_write_b32 v177, v118 offset:13600
	v_mad_u32_u24 v116, v129, s35, v191
	ds_write_b32 v116, v119
	v_bfe_u32 v118, v188, 3, 3
	v_and_b32_e32 v119, 7, v188
	v_lshlrev_b32_e32 v160, 1, v211
	v_add3_u32 v120, v118, s15, v189
	v_mul_u32_u24_e32 v118, 0x110, v118
	v_lshlrev_b32_e32 v119, 5, v119
	v_lshl_add_u64 v[116:117], s[90:91], 0, v[160:161]
	v_and_b32_e32 v160, 0x70, v190
	v_add3_u32 v121, v195, v118, v119
	v_mul_u32_u24_e32 v162, 0x110, v163
	v_mul_u32_u24_e32 v144, 0x110, v145
	v_mul_u32_u24_e32 v128, 0x110, v129
	v_lshl_add_u64 v[116:117], v[116:117], 0, v[160:161]
	v_mov_b32_e32 v122, v121
